# speedup vs baseline: 1.0050x; 1.0050x over previous
; template <int NS, bool LORA, int mat> ...
;     ...
;   const int ch = 64 * head + lane;
;   const float kk_c = p.k_k[ch], ka_c = p.k_a[ch], rk_c = p.r_k[ch];
;   const float mu_r = p.mu_shift[ch], mu_k = p.mu_shift[1024 + ch], mu_v = p.mu_shift[2048 + ch];
;   uint4 la[2][6];
;   u16 rv[2][NS][9];
.LBB0_1118:
	s_lshl_b32 s4, s89, 7
	s_add_i32 s4, s4, s60
	s_lshr_b32 s10, s4, 5
	s_lshl_b64 s[4:5], s[10:11], 11
	s_waitcnt vmcnt(17)
	v_mov_b32 v144, v146
	s_add_u32 s90, s4, 0x4000
	v_ashrrev_i32_e32 v7, 6, v144
	s_waitcnt vmcnt(13)
	v_and_b32_e32 v149, 63, v144
	v_cmp_lt_i32_e32 vcc, 3, v7
	s_and_saveexec_b64 s[4:5], vcc
	s_xor_b64 s[52:53], exec, s[4:5]
	s_cbranch_execz .LBB0_1213
	v_cmp_lt_i32_e32 vcc, 4, v7
	s_and_saveexec_b64 s[4:5], vcc
	s_xor_b64 s[54:55], exec, s[4:5]
	s_cbranch_execz .LBB0_1188
	v_cmp_ne_u32_e32 vcc, 5, v7
	s_and_saveexec_b64 s[4:5], vcc
	s_xor_b64 s[6:7], exec, s[4:5]
	s_cbranch_execz .LBB0_1155
	v_readfirstlane_b32 s4, v7
	v_and_b32_e32 v48, 7, v149
	v_lshrrev_b32_e32 v49, 3, v149
	s_sub_i32 s4, s4, 6
	s_lshl_b32 s4, s4, 3
	v_add_u32_e32 v50, s4, v49
	v_lshl_add_u32 v51, v48, 3, s62
	s_mul_i32 s4, s90, 0x1c00
	v_lshlrev_b32_e32 v52, 1, v51
	v_add_u32_e32 v52, 0x800, v52
	v_add_u32_e32 v52, s4, v52
	v_lshlrev_b32_e32 v51, 2, v51
	v_mov_b32_e32 v53, 0x1c00
	v_mov_b32_e32 v58, 0x7ff
	v_mov_b32_e32 v59, -16
	v_cndmask_b32_e64 v59, v59, 16, s[0:1]
	v_add_u32_e32 v205, 0x1000, v51
	v_add_u32_e32 v206, 0x2000, v51
	global_load_dwordx4 v[0:3], v51, s[50:51]
	global_load_dwordx4 v[4:7], v51, s[50:51] offset:16
	global_load_dwordx4 v[8:11], v51, s[16:17]
	global_load_dwordx4 v[12:15], v51, s[16:17] offset:16
	global_load_dwordx4 v[16:19], v51, s[18:19]
	global_load_dwordx4 v[20:23], v51, s[18:19] offset:16
	global_load_dwordx4 v[24:27], v51, s[38:39]
	global_load_dwordx4 v[28:31], v51, s[38:39] offset:16
	global_load_dwordx4 v[32:35], v205, s[38:39]
	global_load_dwordx4 v[36:39], v205, s[38:39] offset:16
	global_load_dwordx4 v[40:43], v206, s[38:39]
	global_load_dwordx4 v[44:47], v206, s[38:39] offset:16
	v_mul_u32_u24_e32 v54, 0x500, v50
	v_lshlrev_b32_e32 v55, 8, v50
	v_lshl_add_u32 v54, v48, 5, v54
	v_lshl_add_u32 v55, v48, 5, v55
	v_add_u32_e32 v54, 0x5000, v54
	v_add_u32_e32 v55, 0x3000, v55
	v_sub_u32_e32 v205, v58, v50
	v_cndmask_b32_e64 v56, v205, v50, s[0:1]
	v_cmp_eq_u32_e64 s[8:9], 0, v48
	s_waitcnt vmcnt(0)
	v_cmp_lt_i32_e64 s[4:5], 0, v56
	v_cmp_gt_i32_e64 s[58:59], v58, v56
	v_mad_u32_u24 v205, v56, v53, v52
	s_nop 0
	v_cndmask_b32_e64 v206, 0, v53, s[4:5]
	v_cndmask_b32_e64 v207, 0, v53, s[58:59]
	v_cndmask_b32_e64 v60, 0, 1.0, s[4:5]
	v_cndmask_b32_e64 v61, 0, 1.0, s[58:59]
	v_sub_u32_e32 v206, v205, v206
	v_add_u32_e32 v207, v205, v207
	global_load_dwordx4 v[64:67], v205, s[72:73] offset:-2048
	global_load_dwordx4 v[68:71], v205, s[72:73]
	global_load_dwordx4 v[72:75], v205, s[72:73] offset:2048
	global_load_dwordx4 v[76:79], v206, s[72:73] offset:-2048
	global_load_dwordx4 v[80:83], v206, s[72:73]
	global_load_dwordx4 v[84:87], v206, s[72:73] offset:2048
	global_load_dwordx4 v[88:91], v207, s[72:73] offset:-2048
	global_load_dwordx4 v[92:95], v207, s[72:73]
	global_load_dwordx4 v[96:99], v207, s[72:73] offset:2048
	v_add_u32_e32 v57, v59, v56
	v_cmp_lt_i32_e64 s[4:5], 0, v57
	v_cmp_gt_i32_e64 s[58:59], v58, v57
	v_mad_u32_u24 v205, v57, v53, v52
	s_nop 0
	v_cndmask_b32_e64 v206, 0, v53, s[4:5]
	v_cndmask_b32_e64 v207, 0, v53, s[58:59]
	v_cndmask_b32_e64 v62, 0, 1.0, s[4:5]
	v_cndmask_b32_e64 v63, 0, 1.0, s[58:59]
	v_sub_u32_e32 v206, v205, v206
	v_add_u32_e32 v207, v205, v207
	global_load_dwordx4 v[100:103], v205, s[72:73] offset:-2048
	global_load_dwordx4 v[104:107], v205, s[72:73]
	global_load_dwordx4 v[108:111], v205, s[72:73] offset:2048
	global_load_dwordx4 v[112:115], v206, s[72:73] offset:-2048
	global_load_dwordx4 v[116:119], v206, s[72:73]
	global_load_dwordx4 v[120:123], v206, s[72:73] offset:2048
	global_load_dwordx4 v[124:127], v207, s[72:73] offset:-2048
	global_load_dwordx4 v[128:131], v207, s[72:73]
	global_load_dwordx4 v[132:135], v207, s[72:73] offset:2048
	s_mov_b32 s10, 1
	s_waitcnt lgkmcnt(0)
	s_barrier
.Lmy_ks_loop:
	ds_read_b128 v[184:187], v55 offset:0
	ds_read_b128 v[188:191], v55 offset:16
	s_waitcnt vmcnt(9)
	v_lshlrev_b32_e32 v136, 16, v64
	v_lshlrev_b32_e32 v192, 16, v76
	v_lshlrev_b32_e32 v193, 16, v88
	v_mul_f32_e32 v193, v61, v193
	v_fmac_f32_e32 v193, v60, v192
	v_fma_f32 v192, v193, 0.5, -v136
	v_fmac_f32_e32 v136, v24, v192
	v_and_b32_e32 v137, 0xffff0000, v64
	v_and_b32_e32 v192, 0xffff0000, v76
	v_and_b32_e32 v193, 0xffff0000, v88
	v_mul_f32_e32 v193, v61, v193
	v_fmac_f32_e32 v193, v60, v192
	v_fma_f32 v192, v193, 0.5, -v137
	v_fmac_f32_e32 v137, v25, v192
	v_lshlrev_b32_e32 v138, 16, v65
	v_lshlrev_b32_e32 v192, 16, v77
	v_lshlrev_b32_e32 v193, 16, v89
	v_mul_f32_e32 v193, v61, v193
	v_fmac_f32_e32 v193, v60, v192
	v_fma_f32 v192, v193, 0.5, -v138
	v_fmac_f32_e32 v138, v26, v192
	v_and_b32_e32 v139, 0xffff0000, v65
	v_and_b32_e32 v192, 0xffff0000, v77
	v_and_b32_e32 v193, 0xffff0000, v89
	v_mul_f32_e32 v193, v61, v193
	v_fmac_f32_e32 v193, v60, v192
	v_fma_f32 v192, v193, 0.5, -v139
	v_fmac_f32_e32 v139, v27, v192
	v_lshlrev_b32_e32 v140, 16, v66
	v_lshlrev_b32_e32 v192, 16, v78
	v_lshlrev_b32_e32 v193, 16, v90
	v_mul_f32_e32 v193, v61, v193
	v_fmac_f32_e32 v193, v60, v192
	v_fma_f32 v192, v193, 0.5, -v140
	v_fmac_f32_e32 v140, v28, v192
	v_and_b32_e32 v141, 0xffff0000, v66
	v_and_b32_e32 v192, 0xffff0000, v78
	v_and_b32_e32 v193, 0xffff0000, v90
	v_mul_f32_e32 v193, v61, v193
	v_fmac_f32_e32 v193, v60, v192
	v_fma_f32 v192, v193, 0.5, -v141
	v_fmac_f32_e32 v141, v29, v192
	v_lshlrev_b32_e32 v142, 16, v67
	v_lshlrev_b32_e32 v192, 16, v79
	v_lshlrev_b32_e32 v193, 16, v91
	v_mul_f32_e32 v193, v61, v193
	v_fmac_f32_e32 v193, v60, v192
	v_fma_f32 v192, v193, 0.5, -v142
	v_fmac_f32_e32 v142, v30, v192
	v_and_b32_e32 v143, 0xffff0000, v67
	v_and_b32_e32 v192, 0xffff0000, v79
	v_and_b32_e32 v193, 0xffff0000, v91
	v_mul_f32_e32 v193, v61, v193
	v_fmac_f32_e32 v193, v60, v192
	v_fma_f32 v192, v193, 0.5, -v143
	v_fmac_f32_e32 v143, v31, v192
	v_lshlrev_b32_e32 v208, 16, v68
	v_lshlrev_b32_e32 v192, 16, v80
	v_lshlrev_b32_e32 v193, 16, v92
	v_mul_f32_e32 v193, v61, v193
	v_fmac_f32_e32 v193, v60, v192
	v_fma_f32 v192, v193, 0.5, -v208
	v_fmac_f32_e32 v208, v32, v192
	v_and_b32_e32 v209, 0xffff0000, v68
	v_and_b32_e32 v192, 0xffff0000, v80
	v_and_b32_e32 v193, 0xffff0000, v92
	v_mul_f32_e32 v193, v61, v193
	v_fmac_f32_e32 v193, v60, v192
	v_fma_f32 v192, v193, 0.5, -v209
	v_fmac_f32_e32 v209, v33, v192
	v_lshlrev_b32_e32 v210, 16, v69
	v_lshlrev_b32_e32 v192, 16, v81
	v_lshlrev_b32_e32 v193, 16, v93
	v_mul_f32_e32 v193, v61, v193
	v_fmac_f32_e32 v193, v60, v192
	v_fma_f32 v192, v193, 0.5, -v210
	v_fmac_f32_e32 v210, v34, v192
	v_and_b32_e32 v211, 0xffff0000, v69
	v_and_b32_e32 v192, 0xffff0000, v81
	v_and_b32_e32 v193, 0xffff0000, v93
	v_mul_f32_e32 v193, v61, v193
	v_fmac_f32_e32 v193, v60, v192
	v_fma_f32 v192, v193, 0.5, -v211
	v_fmac_f32_e32 v211, v35, v192
	v_lshlrev_b32_e32 v212, 16, v70
	v_lshlrev_b32_e32 v192, 16, v82
	v_lshlrev_b32_e32 v193, 16, v94
	v_mul_f32_e32 v193, v61, v193
	v_fmac_f32_e32 v193, v60, v192
	v_fma_f32 v192, v193, 0.5, -v212
	v_fmac_f32_e32 v212, v36, v192
	v_and_b32_e32 v213, 0xffff0000, v70
	v_and_b32_e32 v192, 0xffff0000, v82
	v_and_b32_e32 v193, 0xffff0000, v94
	v_mul_f32_e32 v193, v61, v193
	v_fmac_f32_e32 v193, v60, v192
	v_fma_f32 v192, v193, 0.5, -v213
	v_fmac_f32_e32 v213, v37, v192
	v_lshlrev_b32_e32 v214, 16, v71
	v_lshlrev_b32_e32 v192, 16, v83
	v_lshlrev_b32_e32 v193, 16, v95
	v_mul_f32_e32 v193, v61, v193
	v_fmac_f32_e32 v193, v60, v192
	v_fma_f32 v192, v193, 0.5, -v214
	v_fmac_f32_e32 v214, v38, v192
	v_and_b32_e32 v215, 0xffff0000, v71
	v_and_b32_e32 v192, 0xffff0000, v83
	v_and_b32_e32 v193, 0xffff0000, v95
	v_mul_f32_e32 v193, v61, v193
	v_fmac_f32_e32 v193, v60, v192
	v_fma_f32 v192, v193, 0.5, -v215
	v_fmac_f32_e32 v215, v39, v192
	v_lshlrev_b32_e32 v152, 16, v72
	v_lshlrev_b32_e32 v192, 16, v84
	v_lshlrev_b32_e32 v193, 16, v96
	v_mul_f32_e32 v193, v61, v193
	v_fmac_f32_e32 v193, v60, v192
	v_fma_f32 v192, v193, 0.5, -v152
	v_fmac_f32_e32 v152, v40, v192
	v_and_b32_e32 v153, 0xffff0000, v72
	v_and_b32_e32 v192, 0xffff0000, v84
	v_and_b32_e32 v193, 0xffff0000, v96
	v_mul_f32_e32 v193, v61, v193
	v_fmac_f32_e32 v193, v60, v192
	v_fma_f32 v192, v193, 0.5, -v153
	v_fmac_f32_e32 v153, v41, v192
	v_lshlrev_b32_e32 v154, 16, v73
	v_lshlrev_b32_e32 v192, 16, v85
	v_lshlrev_b32_e32 v193, 16, v97
	v_mul_f32_e32 v193, v61, v193
	v_fmac_f32_e32 v193, v60, v192
	v_fma_f32 v192, v193, 0.5, -v154
	v_fmac_f32_e32 v154, v42, v192
	v_and_b32_e32 v155, 0xffff0000, v73
	v_and_b32_e32 v192, 0xffff0000, v85
	v_and_b32_e32 v193, 0xffff0000, v97
	v_mul_f32_e32 v193, v61, v193
	v_fmac_f32_e32 v193, v60, v192
	v_fma_f32 v192, v193, 0.5, -v155
	v_fmac_f32_e32 v155, v43, v192
	v_lshlrev_b32_e32 v156, 16, v74
	v_lshlrev_b32_e32 v192, 16, v86
	v_lshlrev_b32_e32 v193, 16, v98
	v_mul_f32_e32 v193, v61, v193
	v_fmac_f32_e32 v193, v60, v192
	v_fma_f32 v192, v193, 0.5, -v156
	v_fmac_f32_e32 v156, v44, v192
	v_and_b32_e32 v157, 0xffff0000, v74
	v_and_b32_e32 v192, 0xffff0000, v86
	v_and_b32_e32 v193, 0xffff0000, v98
	v_mul_f32_e32 v193, v61, v193
	v_fmac_f32_e32 v193, v60, v192
	v_fma_f32 v192, v193, 0.5, -v157
	v_fmac_f32_e32 v157, v45, v192
	v_lshlrev_b32_e32 v158, 16, v75
	v_lshlrev_b32_e32 v192, 16, v87
	v_lshlrev_b32_e32 v193, 16, v99
	v_mul_f32_e32 v193, v61, v193
	v_fmac_f32_e32 v193, v60, v192
	v_fma_f32 v192, v193, 0.5, -v158
	v_fmac_f32_e32 v158, v46, v192
	v_and_b32_e32 v159, 0xffff0000, v75
	v_and_b32_e32 v192, 0xffff0000, v87
	v_and_b32_e32 v193, 0xffff0000, v99
	v_mul_f32_e32 v193, v61, v193
	v_fmac_f32_e32 v193, v60, v192
	v_fma_f32 v192, v193, 0.5, -v159
	v_fmac_f32_e32 v159, v47, v192
	s_cmp_lt_u32 s10, 127
	s_cbranch_scc0 .Lmy_ksa_ni
	v_add_u32_e32 v57, v59, v56
	v_add_u32_e32 v57, v59, v57
	v_cmp_lt_i32_e64 s[4:5], 0, v57
	v_cmp_gt_i32_e64 s[58:59], v58, v57
	v_mad_u32_u24 v205, v57, v53, v52
	s_nop 0
	v_cndmask_b32_e64 v206, 0, v53, s[4:5]
	v_cndmask_b32_e64 v207, 0, v53, s[58:59]
	v_cndmask_b32_e64 v60, 0, 1.0, s[4:5]
	v_cndmask_b32_e64 v61, 0, 1.0, s[58:59]
	v_sub_u32_e32 v206, v205, v206
	v_add_u32_e32 v207, v205, v207
	global_load_dwordx4 v[64:67], v205, s[72:73] offset:-2048
	global_load_dwordx4 v[68:71], v205, s[72:73]
	global_load_dwordx4 v[72:75], v205, s[72:73] offset:2048
	global_load_dwordx4 v[76:79], v206, s[72:73] offset:-2048
	global_load_dwordx4 v[80:83], v206, s[72:73]
	global_load_dwordx4 v[84:87], v206, s[72:73] offset:2048
	global_load_dwordx4 v[88:91], v207, s[72:73] offset:-2048
	global_load_dwordx4 v[92:95], v207, s[72:73]
	global_load_dwordx4 v[96:99], v207, s[72:73] offset:2048
.Lmy_ksa_ni:
	v_mul_f32_e32 v160, v0, v208
	v_mul_f32_e32 v161, v1, v209
	v_mul_f32_e32 v162, v2, v210
	v_mul_f32_e32 v163, v3, v211
	v_mul_f32_e32 v164, v4, v212
	v_mul_f32_e32 v165, v5, v213
	v_mul_f32_e32 v166, v6, v214
	v_mul_f32_e32 v167, v7, v215
	v_mul_f32_e32 v200, v160, v160
	v_fmac_f32_e32 v200, v161, v161
	v_fmac_f32_e32 v200, v162, v162
	v_fmac_f32_e32 v200, v163, v163
	v_fmac_f32_e32 v200, v164, v164
	v_fmac_f32_e32 v200, v165, v165
	v_fmac_f32_e32 v200, v166, v166
	v_fmac_f32_e32 v200, v167, v167
	s_waitcnt lgkmcnt(0)
	v_add_f32_e32 v192, -1.0, v184
	v_fma_f32 v192, v8, v192, 1.0
	v_mul_f32_e32 v176, v208, v192
	v_add_f32_dpp v200, v200, v200 quad_perm:[1,0,3,2] row_mask:0xf bank_mask:0xf bound_ctrl:1
	v_add_f32_e32 v192, -1.0, v185
	v_fma_f32 v192, v9, v192, 1.0
	v_mul_f32_e32 v177, v209, v192
	v_add_f32_dpp v200, v200, v200 quad_perm:[2,3,0,1] row_mask:0xf bank_mask:0xf bound_ctrl:1
	v_add_f32_e32 v192, -1.0, v186
	v_fma_f32 v192, v10, v192, 1.0
	v_mul_f32_e32 v178, v210, v192
	v_add_f32_dpp v200, v200, v200 row_half_mirror row_mask:0xf bank_mask:0xf bound_ctrl:1
	v_add_f32_e32 v192, -1.0, v187
	v_fma_f32 v192, v11, v192, 1.0
	v_mul_f32_e32 v179, v211, v192
	v_add_f32_e32 v192, -1.0, v188
	v_fma_f32 v192, v12, v192, 1.0
	v_mul_f32_e32 v180, v212, v192
	v_add_f32_e32 v192, -1.0, v189
	v_fma_f32 v192, v13, v192, 1.0
	v_mul_f32_e32 v181, v213, v192
	v_add_f32_e32 v192, -1.0, v190
	v_fma_f32 v192, v14, v192, 1.0
	v_mul_f32_e32 v182, v214, v192
	v_add_f32_e32 v192, -1.0, v191
	v_fma_f32 v192, v15, v192, 1.0
	v_mul_f32_e32 v183, v215, v192
	v_max_f32_e32 v200, v200, v200
	v_max_f32_e32 v200, 0x179abe15, v200
	v_rsq_f32_e32 v201, v200
	v_mul_f32_e32 v192, v136, v176
	v_mul_f32_e32 v202, v16, v192
	v_mul_f32_e32 v160, v160, v201
	v_mul_f32_e32 v161, v161, v201
	v_mul_f32_e32 v162, v162, v201
	v_mul_f32_e32 v163, v163, v201
	v_mul_f32_e32 v164, v164, v201
	v_mul_f32_e32 v165, v165, v201
	v_mul_f32_e32 v166, v166, v201
	v_mul_f32_e32 v167, v167, v201
	v_mul_f32_e32 v168, v184, v160
	v_mul_f32_e32 v169, v185, v161
	v_mul_f32_e32 v170, v186, v162
	v_mul_f32_e32 v171, v187, v163
	v_mul_f32_e32 v172, v188, v164
	v_mul_f32_e32 v173, v189, v165
	v_mul_f32_e32 v174, v190, v166
	v_mul_f32_e32 v175, v191, v167
	ds_write_b128 v54, v[160:163] offset:0
	ds_write_b128 v54, v[164:167] offset:16
	ds_write_b128 v54, v[168:171] offset:256
	ds_write_b128 v54, v[172:175] offset:272
	ds_write_b128 v54, v[176:179] offset:512
	ds_write_b128 v54, v[180:183] offset:528
	ds_write_b128 v54, v[136:139] offset:768
	ds_write_b128 v54, v[140:143] offset:784
	ds_write_b128 v54, v[152:155] offset:1024
	ds_write_b128 v54, v[156:159] offset:1040
	v_mul_f32_e32 v192, v137, v177
	v_fmac_f32_e32 v202, v17, v192
	v_mul_f32_e32 v192, v138, v178
	v_fmac_f32_e32 v202, v18, v192
	v_mul_f32_e32 v192, v139, v179
	v_fmac_f32_e32 v202, v19, v192
	v_mul_f32_e32 v192, v140, v180
	v_fmac_f32_e32 v202, v20, v192
	v_mul_f32_e32 v192, v141, v181
	v_fmac_f32_e32 v202, v21, v192
	v_mul_f32_e32 v192, v142, v182
	v_fmac_f32_e32 v202, v22, v192
	v_mul_f32_e32 v192, v143, v183
	v_fmac_f32_e32 v202, v23, v192
	s_nop 1
	v_add_f32_dpp v202, v202, v202 quad_perm:[1,0,3,2] row_mask:0xf bank_mask:0xf bound_ctrl:1
	s_nop 1
	v_add_f32_dpp v202, v202, v202 quad_perm:[2,3,0,1] row_mask:0xf bank_mask:0xf bound_ctrl:1
	s_nop 1
	v_add_f32_dpp v202, v202, v202 row_half_mirror row_mask:0xf bank_mask:0xf bound_ctrl:1
	v_add_u32_e32 v205, s90, v56
	v_lshl_add_u32 v205, v205, 7, s64
	s_and_saveexec_b64 s[56:57], s[8:9]
	global_store_dword v205, v202, s[24:25]
	s_or_b64 exec, exec, s[56:57]
	v_add_u32_e32 v56, v59, v56
	s_waitcnt lgkmcnt(0)
	s_barrier
	s_add_i32 s10, s10, 1
	ds_read_b128 v[184:187], v55 offset:4096
	ds_read_b128 v[188:191], v55 offset:4112
	s_cmp_lt_u32 s10, 128
	s_cbranch_scc0 .Lmy_ksb_w0
	s_waitcnt vmcnt(9)
	s_branch .Lmy_ksb_w1

.Lmy_ksb_w1:
	v_lshlrev_b32_e32 v136, 16, v100
	v_lshlrev_b32_e32 v192, 16, v112
	v_lshlrev_b32_e32 v193, 16, v124
	v_mul_f32_e32 v193, v63, v193
	v_fmac_f32_e32 v193, v62, v192
	v_fma_f32 v192, v193, 0.5, -v136
	v_fmac_f32_e32 v136, v24, v192
	v_and_b32_e32 v137, 0xffff0000, v100
	v_and_b32_e32 v192, 0xffff0000, v112
	v_and_b32_e32 v193, 0xffff0000, v124
	v_mul_f32_e32 v193, v63, v193
	v_fmac_f32_e32 v193, v62, v192
	v_fma_f32 v192, v193, 0.5, -v137
	v_fmac_f32_e32 v137, v25, v192
	v_lshlrev_b32_e32 v138, 16, v101
	v_lshlrev_b32_e32 v192, 16, v113
	v_lshlrev_b32_e32 v193, 16, v125
	v_mul_f32_e32 v193, v63, v193
	v_fmac_f32_e32 v193, v62, v192
	v_fma_f32 v192, v193, 0.5, -v138
	v_fmac_f32_e32 v138, v26, v192
	v_and_b32_e32 v139, 0xffff0000, v101
	v_and_b32_e32 v192, 0xffff0000, v113
	v_and_b32_e32 v193, 0xffff0000, v125
	v_mul_f32_e32 v193, v63, v193
	v_fmac_f32_e32 v193, v62, v192
	v_fma_f32 v192, v193, 0.5, -v139
	v_fmac_f32_e32 v139, v27, v192
	v_lshlrev_b32_e32 v140, 16, v102
	v_lshlrev_b32_e32 v192, 16, v114
	v_lshlrev_b32_e32 v193, 16, v126
	v_mul_f32_e32 v193, v63, v193
	v_fmac_f32_e32 v193, v62, v192
	v_fma_f32 v192, v193, 0.5, -v140
	v_fmac_f32_e32 v140, v28, v192
	v_and_b32_e32 v141, 0xffff0000, v102
	v_and_b32_e32 v192, 0xffff0000, v114
	v_and_b32_e32 v193, 0xffff0000, v126
	v_mul_f32_e32 v193, v63, v193
	v_fmac_f32_e32 v193, v62, v192
	v_fma_f32 v192, v193, 0.5, -v141
	v_fmac_f32_e32 v141, v29, v192
	v_lshlrev_b32_e32 v142, 16, v103
	v_lshlrev_b32_e32 v192, 16, v115
	v_lshlrev_b32_e32 v193, 16, v127
	v_mul_f32_e32 v193, v63, v193
	v_fmac_f32_e32 v193, v62, v192
	v_fma_f32 v192, v193, 0.5, -v142
	v_fmac_f32_e32 v142, v30, v192
	v_and_b32_e32 v143, 0xffff0000, v103
	v_and_b32_e32 v192, 0xffff0000, v115
	v_and_b32_e32 v193, 0xffff0000, v127
	v_mul_f32_e32 v193, v63, v193
	v_fmac_f32_e32 v193, v62, v192
	v_fma_f32 v192, v193, 0.5, -v143
	v_fmac_f32_e32 v143, v31, v192
	v_lshlrev_b32_e32 v208, 16, v104
	v_lshlrev_b32_e32 v192, 16, v116
	v_lshlrev_b32_e32 v193, 16, v128
	v_mul_f32_e32 v193, v63, v193
	v_fmac_f32_e32 v193, v62, v192
	v_fma_f32 v192, v193, 0.5, -v208
	v_fmac_f32_e32 v208, v32, v192
	v_and_b32_e32 v209, 0xffff0000, v104
	v_and_b32_e32 v192, 0xffff0000, v116
	v_and_b32_e32 v193, 0xffff0000, v128
	v_mul_f32_e32 v193, v63, v193
	v_fmac_f32_e32 v193, v62, v192
	v_fma_f32 v192, v193, 0.5, -v209
	v_fmac_f32_e32 v209, v33, v192
	v_lshlrev_b32_e32 v210, 16, v105
	v_lshlrev_b32_e32 v192, 16, v117
	v_lshlrev_b32_e32 v193, 16, v129
	v_mul_f32_e32 v193, v63, v193
	v_fmac_f32_e32 v193, v62, v192
	v_fma_f32 v192, v193, 0.5, -v210
	v_fmac_f32_e32 v210, v34, v192
	v_and_b32_e32 v211, 0xffff0000, v105
	v_and_b32_e32 v192, 0xffff0000, v117
	v_and_b32_e32 v193, 0xffff0000, v129
	v_mul_f32_e32 v193, v63, v193
	v_fmac_f32_e32 v193, v62, v192
	v_fma_f32 v192, v193, 0.5, -v211
	v_fmac_f32_e32 v211, v35, v192
	v_lshlrev_b32_e32 v212, 16, v106
	v_lshlrev_b32_e32 v192, 16, v118
	v_lshlrev_b32_e32 v193, 16, v130
	v_mul_f32_e32 v193, v63, v193
	v_fmac_f32_e32 v193, v62, v192
	v_fma_f32 v192, v193, 0.5, -v212
	v_fmac_f32_e32 v212, v36, v192
	v_and_b32_e32 v213, 0xffff0000, v106
	v_and_b32_e32 v192, 0xffff0000, v118
	v_and_b32_e32 v193, 0xffff0000, v130
	v_mul_f32_e32 v193, v63, v193
	v_fmac_f32_e32 v193, v62, v192
	v_fma_f32 v192, v193, 0.5, -v213
	v_fmac_f32_e32 v213, v37, v192
	v_lshlrev_b32_e32 v214, 16, v107
	v_lshlrev_b32_e32 v192, 16, v119
	v_lshlrev_b32_e32 v193, 16, v131
	v_mul_f32_e32 v193, v63, v193
	v_fmac_f32_e32 v193, v62, v192
	v_fma_f32 v192, v193, 0.5, -v214
	v_fmac_f32_e32 v214, v38, v192
	v_and_b32_e32 v215, 0xffff0000, v107
	v_and_b32_e32 v192, 0xffff0000, v119
	v_and_b32_e32 v193, 0xffff0000, v131
	v_mul_f32_e32 v193, v63, v193
	v_fmac_f32_e32 v193, v62, v192
	v_fma_f32 v192, v193, 0.5, -v215
	v_fmac_f32_e32 v215, v39, v192
	v_lshlrev_b32_e32 v152, 16, v108
	v_lshlrev_b32_e32 v192, 16, v120
	v_lshlrev_b32_e32 v193, 16, v132
	v_mul_f32_e32 v193, v63, v193
	v_fmac_f32_e32 v193, v62, v192
	v_fma_f32 v192, v193, 0.5, -v152
	v_fmac_f32_e32 v152, v40, v192
	v_and_b32_e32 v153, 0xffff0000, v108
	v_and_b32_e32 v192, 0xffff0000, v120
	v_and_b32_e32 v193, 0xffff0000, v132
	v_mul_f32_e32 v193, v63, v193
	v_fmac_f32_e32 v193, v62, v192
	v_fma_f32 v192, v193, 0.5, -v153
	v_fmac_f32_e32 v153, v41, v192
	v_lshlrev_b32_e32 v154, 16, v109
	v_lshlrev_b32_e32 v192, 16, v121
	v_lshlrev_b32_e32 v193, 16, v133
	v_mul_f32_e32 v193, v63, v193
	v_fmac_f32_e32 v193, v62, v192
	v_fma_f32 v192, v193, 0.5, -v154
	v_fmac_f32_e32 v154, v42, v192
	v_and_b32_e32 v155, 0xffff0000, v109
	v_and_b32_e32 v192, 0xffff0000, v121
	v_and_b32_e32 v193, 0xffff0000, v133
	v_mul_f32_e32 v193, v63, v193
	v_fmac_f32_e32 v193, v62, v192
	v_fma_f32 v192, v193, 0.5, -v155
	v_fmac_f32_e32 v155, v43, v192
	v_lshlrev_b32_e32 v156, 16, v110
	v_lshlrev_b32_e32 v192, 16, v122
	v_lshlrev_b32_e32 v193, 16, v134
	v_mul_f32_e32 v193, v63, v193
	v_fmac_f32_e32 v193, v62, v192
	v_fma_f32 v192, v193, 0.5, -v156
	v_fmac_f32_e32 v156, v44, v192
	v_and_b32_e32 v157, 0xffff0000, v110
	v_and_b32_e32 v192, 0xffff0000, v122
	v_and_b32_e32 v193, 0xffff0000, v134
	v_mul_f32_e32 v193, v63, v193
	v_fmac_f32_e32 v193, v62, v192
	v_fma_f32 v192, v193, 0.5, -v157
	v_fmac_f32_e32 v157, v45, v192
	v_lshlrev_b32_e32 v158, 16, v111
	v_lshlrev_b32_e32 v192, 16, v123
	v_lshlrev_b32_e32 v193, 16, v135
	v_mul_f32_e32 v193, v63, v193
	v_fmac_f32_e32 v193, v62, v192
	v_fma_f32 v192, v193, 0.5, -v158
	v_fmac_f32_e32 v158, v46, v192
	v_and_b32_e32 v159, 0xffff0000, v111
	v_and_b32_e32 v192, 0xffff0000, v123
	v_and_b32_e32 v193, 0xffff0000, v135
	v_mul_f32_e32 v193, v63, v193
	v_fmac_f32_e32 v193, v62, v192
	v_fma_f32 v192, v193, 0.5, -v159
	v_fmac_f32_e32 v159, v47, v192
	s_cmp_lt_u32 s10, 127
	s_cbranch_scc0 .Lmy_ksb_ni
	v_add_u32_e32 v57, v59, v56
	v_add_u32_e32 v57, v59, v57
	v_cmp_lt_i32_e64 s[4:5], 0, v57
	v_cmp_gt_i32_e64 s[58:59], v58, v57
	v_mad_u32_u24 v205, v57, v53, v52
	s_nop 0
	v_cndmask_b32_e64 v206, 0, v53, s[4:5]
	v_cndmask_b32_e64 v207, 0, v53, s[58:59]
	v_cndmask_b32_e64 v62, 0, 1.0, s[4:5]
	v_cndmask_b32_e64 v63, 0, 1.0, s[58:59]
	v_sub_u32_e32 v206, v205, v206
	v_add_u32_e32 v207, v205, v207
	global_load_dwordx4 v[100:103], v205, s[72:73] offset:-2048
	global_load_dwordx4 v[104:107], v205, s[72:73]
	global_load_dwordx4 v[108:111], v205, s[72:73] offset:2048
	global_load_dwordx4 v[112:115], v206, s[72:73] offset:-2048
	global_load_dwordx4 v[116:119], v206, s[72:73]
	global_load_dwordx4 v[120:123], v206, s[72:73] offset:2048
	global_load_dwordx4 v[124:127], v207, s[72:73] offset:-2048
	global_load_dwordx4 v[128:131], v207, s[72:73]
	global_load_dwordx4 v[132:135], v207, s[72:73] offset:2048
.Lmy_ksb_ni:
	v_mul_f32_e32 v160, v0, v208
	v_mul_f32_e32 v161, v1, v209
	v_mul_f32_e32 v162, v2, v210
	v_mul_f32_e32 v163, v3, v211
	v_mul_f32_e32 v164, v4, v212
	v_mul_f32_e32 v165, v5, v213
	v_mul_f32_e32 v166, v6, v214
	v_mul_f32_e32 v167, v7, v215
	v_mul_f32_e32 v200, v160, v160
	v_fmac_f32_e32 v200, v161, v161
	v_fmac_f32_e32 v200, v162, v162
	v_fmac_f32_e32 v200, v163, v163
	v_fmac_f32_e32 v200, v164, v164
	v_fmac_f32_e32 v200, v165, v165
	v_fmac_f32_e32 v200, v166, v166
	v_fmac_f32_e32 v200, v167, v167
	s_waitcnt lgkmcnt(0)
	v_add_f32_e32 v192, -1.0, v184
	v_fma_f32 v192, v8, v192, 1.0
	v_mul_f32_e32 v176, v208, v192
	v_add_f32_dpp v200, v200, v200 quad_perm:[1,0,3,2] row_mask:0xf bank_mask:0xf bound_ctrl:1
	v_add_f32_e32 v192, -1.0, v185
	v_fma_f32 v192, v9, v192, 1.0
	v_mul_f32_e32 v177, v209, v192
	v_add_f32_dpp v200, v200, v200 quad_perm:[2,3,0,1] row_mask:0xf bank_mask:0xf bound_ctrl:1
	v_add_f32_e32 v192, -1.0, v186
	v_fma_f32 v192, v10, v192, 1.0
	v_mul_f32_e32 v178, v210, v192
	v_add_f32_dpp v200, v200, v200 row_half_mirror row_mask:0xf bank_mask:0xf bound_ctrl:1
	v_add_f32_e32 v192, -1.0, v187
	v_fma_f32 v192, v11, v192, 1.0
	v_mul_f32_e32 v179, v211, v192
	v_add_f32_e32 v192, -1.0, v188
	v_fma_f32 v192, v12, v192, 1.0
	v_mul_f32_e32 v180, v212, v192
	v_add_f32_e32 v192, -1.0, v189
	v_fma_f32 v192, v13, v192, 1.0
	v_mul_f32_e32 v181, v213, v192
	v_add_f32_e32 v192, -1.0, v190
	v_fma_f32 v192, v14, v192, 1.0
	v_mul_f32_e32 v182, v214, v192
	v_add_f32_e32 v192, -1.0, v191
	v_fma_f32 v192, v15, v192, 1.0
	v_mul_f32_e32 v183, v215, v192
	v_max_f32_e32 v200, v200, v200
	v_max_f32_e32 v200, 0x179abe15, v200
	v_rsq_f32_e32 v201, v200
	v_mul_f32_e32 v192, v136, v176
	v_mul_f32_e32 v202, v16, v192
	v_mul_f32_e32 v160, v160, v201
	v_mul_f32_e32 v161, v161, v201
	v_mul_f32_e32 v162, v162, v201
	v_mul_f32_e32 v163, v163, v201
	v_mul_f32_e32 v164, v164, v201
	v_mul_f32_e32 v165, v165, v201
	v_mul_f32_e32 v166, v166, v201
	v_mul_f32_e32 v167, v167, v201
	v_mul_f32_e32 v168, v184, v160
	v_mul_f32_e32 v169, v185, v161
	v_mul_f32_e32 v170, v186, v162
	v_mul_f32_e32 v171, v187, v163
	v_mul_f32_e32 v172, v188, v164
	v_mul_f32_e32 v173, v189, v165
	v_mul_f32_e32 v174, v190, v166
	v_mul_f32_e32 v175, v191, v167
	ds_write_b128 v54, v[160:163] offset:20480
	ds_write_b128 v54, v[164:167] offset:20496
	ds_write_b128 v54, v[168:171] offset:20736
	ds_write_b128 v54, v[172:175] offset:20752
	ds_write_b128 v54, v[176:179] offset:20992
	ds_write_b128 v54, v[180:183] offset:21008
	ds_write_b128 v54, v[136:139] offset:21248
	ds_write_b128 v54, v[140:143] offset:21264
	ds_write_b128 v54, v[152:155] offset:21504
	ds_write_b128 v54, v[156:159] offset:21520
	v_mul_f32_e32 v192, v137, v177
	v_fmac_f32_e32 v202, v17, v192
	v_mul_f32_e32 v192, v138, v178
	v_fmac_f32_e32 v202, v18, v192
	v_mul_f32_e32 v192, v139, v179
	v_fmac_f32_e32 v202, v19, v192
	v_mul_f32_e32 v192, v140, v180
	v_fmac_f32_e32 v202, v20, v192
	v_mul_f32_e32 v192, v141, v181
	v_fmac_f32_e32 v202, v21, v192
	v_mul_f32_e32 v192, v142, v182
	v_fmac_f32_e32 v202, v22, v192
	v_mul_f32_e32 v192, v143, v183
	v_fmac_f32_e32 v202, v23, v192
	s_nop 1
	v_add_f32_dpp v202, v202, v202 quad_perm:[1,0,3,2] row_mask:0xf bank_mask:0xf bound_ctrl:1
	s_nop 1
	v_add_f32_dpp v202, v202, v202 quad_perm:[2,3,0,1] row_mask:0xf bank_mask:0xf bound_ctrl:1
	s_nop 1
	v_add_f32_dpp v202, v202, v202 row_half_mirror row_mask:0xf bank_mask:0xf bound_ctrl:1
	v_add_u32_e32 v205, s90, v56
	v_lshl_add_u32 v205, v205, 7, s64
	s_and_saveexec_b64 s[56:57], s[8:9]
	global_store_dword v205, v202, s[24:25]
	s_or_b64 exec, exec, s[56:57]
	v_add_u32_e32 v56, v59, v56
	s_waitcnt lgkmcnt(0)
	s_barrier
	s_add_i32 s10, s10, 1
	s_cmp_lt_u32 s10, 129
	s_cbranch_scc1 .Lmy_ks_loop
	s_waitcnt lgkmcnt(0)
	s_barrier

; template <int NS, bool LORA, int mat> ...
;     ...
;   const int ch = 64 * head + lane;
;   const float kk_c = p.k_k[ch], ka_c = p.k_a[ch], rk_c = p.r_k[ch];
;   const float mu_r = p.mu_shift[ch], mu_k = p.mu_shift[1024 + ch], mu_v = p.mu_shift[2048 + ch];
;   uint4 la[2][6];
;   u16 rv[2][NS][9];
; __device__ __forceinline__ void scan_run_job(const Params& p, float* lds, int job) {
;   if (job < 128) {
;     const int chain = job >> 2, q = job & 3;
;     scan_job<1, 2>(p, lds, 0, 16384, chain >> 1, chain & 1, q * 16, q);
.LBB0_1226:
	s_andn2_b64 vcc, exec, s[0:1]
	s_cbranch_vccnz .LBB0_1354
	s_ashr_i32 s0, s2, 3
	s_add_i32 s4, s3, s0
	s_and_b32 s3, s0, 3
	s_ashr_i32 s59, s4, 3
	s_bfe_u32 s58, s0, 0x10002
	s_cmp_eq_u32 s58, 0
	s_waitcnt vmcnt(7)
	v_mov_b32 v140, v146
	s_cselect_b64 s[0:1], -1, 0
	s_waitcnt vmcnt(0)
	v_ashrrev_i32_e32 v6, 6, v140
	v_and_b32_e32 v148, 63, v140
	v_cmp_lt_i32_e32 vcc, 3, v6
	s_and_saveexec_b64 s[6:7], vcc
	s_xor_b64 s[46:47], exec, s[6:7]
	s_cbranch_execz .LBB0_1346
	s_lshl_b32 s61, s59, 6
	s_lshl_b32 s63, s58, 6
	s_lshl_b32 s5, s58, 10
	s_ashr_i32 s6, s61, 31
	s_add_u32 s64, s61, s5
	s_addc_u32 s65, s6, 0
	s_add_i32 s62, s61, s5
	s_and_b32 s4, s4, -8
	s_lshl_b32 s5, s58, 2
	s_or_b32 s60, s5, s4
	v_cmp_lt_i32_e32 vcc, 4, v6
	s_and_saveexec_b64 s[4:5], vcc
	s_xor_b64 s[48:49], exec, s[4:5]
	s_cbranch_execz .LBB0_1319
	v_cmp_ne_u32_e32 vcc, 5, v6
	s_and_saveexec_b64 s[4:5], vcc
	s_xor_b64 s[52:53], exec, s[4:5]
	s_cbranch_execz .LBB0_1276
	v_readfirstlane_b32 s4, v6
	v_and_b32_e32 v48, 7, v148
	v_lshrrev_b32_e32 v49, 3, v148
	s_sub_i32 s4, s4, 6
	s_lshl_b32 s4, s4, 3
	v_add_u32_e32 v50, s4, v49
	v_lshl_add_u32 v51, v48, 3, s61
	v_lshlrev_b32_e32 v52, 1, v51
	v_add_u32_e32 v52, 0x800, v52
	v_lshlrev_b32_e32 v51, 2, v51
	v_mov_b32_e32 v53, 0x1c00
	v_mov_b32_e32 v58, 0x3fff
	v_mov_b32_e32 v59, -16
	v_cndmask_b32_e64 v59, v59, 16, s[0:1]
	v_add_u32_e32 v205, 0x1000, v51
	v_add_u32_e32 v206, 0x2000, v51
	global_load_dwordx4 v[0:3], v51, s[50:51]
	global_load_dwordx4 v[4:7], v51, s[50:51] offset:16
	global_load_dwordx4 v[8:11], v51, s[16:17]
	global_load_dwordx4 v[12:15], v51, s[16:17] offset:16
	global_load_dwordx4 v[16:19], v51, s[18:19]
	global_load_dwordx4 v[20:23], v51, s[18:19] offset:16
	global_load_dwordx4 v[24:27], v51, s[38:39]
	global_load_dwordx4 v[28:31], v51, s[38:39] offset:16
	global_load_dwordx4 v[32:35], v205, s[38:39]
	global_load_dwordx4 v[36:39], v205, s[38:39] offset:16
	global_load_dwordx4 v[40:43], v206, s[38:39]
	global_load_dwordx4 v[44:47], v206, s[38:39] offset:16
	v_mul_u32_u24_e32 v54, 0x500, v50
	v_lshlrev_b32_e32 v55, 8, v50
	v_lshl_add_u32 v54, v48, 5, v54
	v_lshl_add_u32 v55, v48, 5, v55
	v_add_u32_e32 v54, 0x5000, v54
	v_add_u32_e32 v55, 0x3000, v55
	v_sub_u32_e32 v205, v58, v50
	v_cndmask_b32_e64 v56, v205, v50, s[0:1]
	v_and_b32_e32 v205, 3, v50
	v_cmp_eq_u32_e64 s[8:9], s3, v205
	v_cmp_eq_u32_e32 vcc, 0, v48
	s_and_b64 s[8:9], s[8:9], vcc
	s_waitcnt vmcnt(0)
	v_cmp_lt_i32_e64 s[10:11], 0, v56
	v_cmp_gt_i32_e64 s[12:13], v58, v56
	v_mad_u32_u24 v205, v56, v53, v52
	s_nop 0
	v_cndmask_b32_e64 v206, 0, v53, s[10:11]
	v_cndmask_b32_e64 v207, 0, v53, s[12:13]
	v_cndmask_b32_e64 v60, 0, 1.0, s[10:11]
	v_cndmask_b32_e64 v61, 0, 1.0, s[12:13]
	v_sub_u32_e32 v206, v205, v206
	v_add_u32_e32 v207, v205, v207
	global_load_dwordx4 v[64:67], v205, s[72:73] offset:-2048
	global_load_dwordx4 v[68:71], v205, s[72:73]
	global_load_dwordx4 v[72:75], v205, s[72:73] offset:2048
	global_load_dwordx4 v[76:79], v206, s[72:73] offset:-2048
	global_load_dwordx4 v[80:83], v206, s[72:73]
	global_load_dwordx4 v[84:87], v206, s[72:73] offset:2048
	global_load_dwordx4 v[88:91], v207, s[72:73] offset:-2048
	global_load_dwordx4 v[92:95], v207, s[72:73]
	global_load_dwordx4 v[96:99], v207, s[72:73] offset:2048
	v_add_u32_e32 v57, v59, v56
	v_cmp_lt_i32_e64 s[10:11], 0, v57
	v_cmp_gt_i32_e64 s[12:13], v58, v57
	v_mad_u32_u24 v205, v57, v53, v52
	s_nop 0
	v_cndmask_b32_e64 v206, 0, v53, s[10:11]
	v_cndmask_b32_e64 v207, 0, v53, s[12:13]
	v_cndmask_b32_e64 v62, 0, 1.0, s[10:11]
	v_cndmask_b32_e64 v63, 0, 1.0, s[12:13]
	v_sub_u32_e32 v206, v205, v206
	v_add_u32_e32 v207, v205, v207
	global_load_dwordx4 v[100:103], v205, s[72:73] offset:-2048
	global_load_dwordx4 v[104:107], v205, s[72:73]
	global_load_dwordx4 v[108:111], v205, s[72:73] offset:2048
	global_load_dwordx4 v[112:115], v206, s[72:73] offset:-2048
	global_load_dwordx4 v[116:119], v206, s[72:73]
	global_load_dwordx4 v[120:123], v206, s[72:73] offset:2048
	global_load_dwordx4 v[124:127], v207, s[72:73] offset:-2048
	global_load_dwordx4 v[128:131], v207, s[72:73]
	global_load_dwordx4 v[132:135], v207, s[72:73] offset:2048
	s_mov_b32 s66, 1
	s_waitcnt lgkmcnt(0)
	s_barrier
.Lmy_kp_loop:
	ds_read_b128 v[184:187], v55 offset:0
	ds_read_b128 v[188:191], v55 offset:16
	s_waitcnt vmcnt(9)
	v_lshlrev_b32_e32 v136, 16, v64
	v_lshlrev_b32_e32 v192, 16, v76
	v_lshlrev_b32_e32 v193, 16, v88
	v_mul_f32_e32 v193, v61, v193
	v_fmac_f32_e32 v193, v60, v192
	v_fma_f32 v192, v193, 0.5, -v136
	v_fmac_f32_e32 v136, v24, v192
	v_and_b32_e32 v137, 0xffff0000, v64
	v_and_b32_e32 v192, 0xffff0000, v76
	v_and_b32_e32 v193, 0xffff0000, v88
	v_mul_f32_e32 v193, v61, v193
	v_fmac_f32_e32 v193, v60, v192
	v_fma_f32 v192, v193, 0.5, -v137
	v_fmac_f32_e32 v137, v25, v192
	v_lshlrev_b32_e32 v138, 16, v65
	v_lshlrev_b32_e32 v192, 16, v77
	v_lshlrev_b32_e32 v193, 16, v89
	v_mul_f32_e32 v193, v61, v193
	v_fmac_f32_e32 v193, v60, v192
	v_fma_f32 v192, v193, 0.5, -v138
	v_fmac_f32_e32 v138, v26, v192
	v_and_b32_e32 v139, 0xffff0000, v65
	v_and_b32_e32 v192, 0xffff0000, v77
	v_and_b32_e32 v193, 0xffff0000, v89
	v_mul_f32_e32 v193, v61, v193
	v_fmac_f32_e32 v193, v60, v192
	v_fma_f32 v192, v193, 0.5, -v139
	v_fmac_f32_e32 v139, v27, v192
	v_lshlrev_b32_e32 v140, 16, v66
	v_lshlrev_b32_e32 v192, 16, v78
	v_lshlrev_b32_e32 v193, 16, v90
	v_mul_f32_e32 v193, v61, v193
	v_fmac_f32_e32 v193, v60, v192
	v_fma_f32 v192, v193, 0.5, -v140
	v_fmac_f32_e32 v140, v28, v192
	v_and_b32_e32 v141, 0xffff0000, v66
	v_and_b32_e32 v192, 0xffff0000, v78
	v_and_b32_e32 v193, 0xffff0000, v90
	v_mul_f32_e32 v193, v61, v193
	v_fmac_f32_e32 v193, v60, v192
	v_fma_f32 v192, v193, 0.5, -v141
	v_fmac_f32_e32 v141, v29, v192
	v_lshlrev_b32_e32 v142, 16, v67
	v_lshlrev_b32_e32 v192, 16, v79
	v_lshlrev_b32_e32 v193, 16, v91
	v_mul_f32_e32 v193, v61, v193
	v_fmac_f32_e32 v193, v60, v192
	v_fma_f32 v192, v193, 0.5, -v142
	v_fmac_f32_e32 v142, v30, v192
	v_and_b32_e32 v143, 0xffff0000, v67
	v_and_b32_e32 v192, 0xffff0000, v79
	v_and_b32_e32 v193, 0xffff0000, v91
	v_mul_f32_e32 v193, v61, v193
	v_fmac_f32_e32 v193, v60, v192
	v_fma_f32 v192, v193, 0.5, -v143
	v_fmac_f32_e32 v143, v31, v192
	v_lshlrev_b32_e32 v208, 16, v68
	v_lshlrev_b32_e32 v192, 16, v80
	v_lshlrev_b32_e32 v193, 16, v92
	v_mul_f32_e32 v193, v61, v193
	v_fmac_f32_e32 v193, v60, v192
	v_fma_f32 v192, v193, 0.5, -v208
	v_fmac_f32_e32 v208, v32, v192
	v_and_b32_e32 v209, 0xffff0000, v68
	v_and_b32_e32 v192, 0xffff0000, v80
	v_and_b32_e32 v193, 0xffff0000, v92
	v_mul_f32_e32 v193, v61, v193
	v_fmac_f32_e32 v193, v60, v192
	v_fma_f32 v192, v193, 0.5, -v209
	v_fmac_f32_e32 v209, v33, v192
	v_lshlrev_b32_e32 v210, 16, v69
	v_lshlrev_b32_e32 v192, 16, v81
	v_lshlrev_b32_e32 v193, 16, v93
	v_mul_f32_e32 v193, v61, v193
	v_fmac_f32_e32 v193, v60, v192
	v_fma_f32 v192, v193, 0.5, -v210
	v_fmac_f32_e32 v210, v34, v192
	v_and_b32_e32 v211, 0xffff0000, v69
	v_and_b32_e32 v192, 0xffff0000, v81
	v_and_b32_e32 v193, 0xffff0000, v93
	v_mul_f32_e32 v193, v61, v193
	v_fmac_f32_e32 v193, v60, v192
	v_fma_f32 v192, v193, 0.5, -v211
	v_fmac_f32_e32 v211, v35, v192
	v_lshlrev_b32_e32 v212, 16, v70
	v_lshlrev_b32_e32 v192, 16, v82
	v_lshlrev_b32_e32 v193, 16, v94
	v_mul_f32_e32 v193, v61, v193
	v_fmac_f32_e32 v193, v60, v192
	v_fma_f32 v192, v193, 0.5, -v212
	v_fmac_f32_e32 v212, v36, v192
	v_and_b32_e32 v213, 0xffff0000, v70
	v_and_b32_e32 v192, 0xffff0000, v82
	v_and_b32_e32 v193, 0xffff0000, v94
	v_mul_f32_e32 v193, v61, v193
	v_fmac_f32_e32 v193, v60, v192
	v_fma_f32 v192, v193, 0.5, -v213
	v_fmac_f32_e32 v213, v37, v192
	v_lshlrev_b32_e32 v214, 16, v71
	v_lshlrev_b32_e32 v192, 16, v83
	v_lshlrev_b32_e32 v193, 16, v95
	v_mul_f32_e32 v193, v61, v193
	v_fmac_f32_e32 v193, v60, v192
	v_fma_f32 v192, v193, 0.5, -v214
	v_fmac_f32_e32 v214, v38, v192
	v_and_b32_e32 v215, 0xffff0000, v71
	v_and_b32_e32 v192, 0xffff0000, v83
	v_and_b32_e32 v193, 0xffff0000, v95
	v_mul_f32_e32 v193, v61, v193
	v_fmac_f32_e32 v193, v60, v192
	v_fma_f32 v192, v193, 0.5, -v215
	v_fmac_f32_e32 v215, v39, v192
	v_lshlrev_b32_e32 v152, 16, v72
	v_lshlrev_b32_e32 v192, 16, v84
	v_lshlrev_b32_e32 v193, 16, v96
	v_mul_f32_e32 v193, v61, v193
	v_fmac_f32_e32 v193, v60, v192
	v_fma_f32 v192, v193, 0.5, -v152
	v_fmac_f32_e32 v152, v40, v192
	v_and_b32_e32 v153, 0xffff0000, v72
	v_and_b32_e32 v192, 0xffff0000, v84
	v_and_b32_e32 v193, 0xffff0000, v96
	v_mul_f32_e32 v193, v61, v193
	v_fmac_f32_e32 v193, v60, v192
	v_fma_f32 v192, v193, 0.5, -v153
	v_fmac_f32_e32 v153, v41, v192
	v_lshlrev_b32_e32 v154, 16, v73
	v_lshlrev_b32_e32 v192, 16, v85
	v_lshlrev_b32_e32 v193, 16, v97
	v_mul_f32_e32 v193, v61, v193
	v_fmac_f32_e32 v193, v60, v192
	v_fma_f32 v192, v193, 0.5, -v154
	v_fmac_f32_e32 v154, v42, v192
	v_and_b32_e32 v155, 0xffff0000, v73
	v_and_b32_e32 v192, 0xffff0000, v85
	v_and_b32_e32 v193, 0xffff0000, v97
	v_mul_f32_e32 v193, v61, v193
	v_fmac_f32_e32 v193, v60, v192
	v_fma_f32 v192, v193, 0.5, -v155
	v_fmac_f32_e32 v155, v43, v192
	v_lshlrev_b32_e32 v156, 16, v74
	v_lshlrev_b32_e32 v192, 16, v86
	v_lshlrev_b32_e32 v193, 16, v98
	v_mul_f32_e32 v193, v61, v193
	v_fmac_f32_e32 v193, v60, v192
	v_fma_f32 v192, v193, 0.5, -v156
	v_fmac_f32_e32 v156, v44, v192
	v_and_b32_e32 v157, 0xffff0000, v74
	v_and_b32_e32 v192, 0xffff0000, v86
	v_and_b32_e32 v193, 0xffff0000, v98
	v_mul_f32_e32 v193, v61, v193
	v_fmac_f32_e32 v193, v60, v192
	v_fma_f32 v192, v193, 0.5, -v157
	v_fmac_f32_e32 v157, v45, v192
	v_lshlrev_b32_e32 v158, 16, v75
	v_lshlrev_b32_e32 v192, 16, v87
	v_lshlrev_b32_e32 v193, 16, v99
	v_mul_f32_e32 v193, v61, v193
	v_fmac_f32_e32 v193, v60, v192
	v_fma_f32 v192, v193, 0.5, -v158
	v_fmac_f32_e32 v158, v46, v192
	v_and_b32_e32 v159, 0xffff0000, v75
	v_and_b32_e32 v192, 0xffff0000, v87
	v_and_b32_e32 v193, 0xffff0000, v99
	v_mul_f32_e32 v193, v61, v193
	v_fmac_f32_e32 v193, v60, v192
	v_fma_f32 v192, v193, 0.5, -v159
	v_fmac_f32_e32 v159, v47, v192
	s_cmp_lt_u32 s66, 1023
	s_cbranch_scc0 .Lmy_kpa_ni
	v_add_u32_e32 v57, v59, v56
	v_add_u32_e32 v57, v59, v57
	v_cmp_lt_i32_e64 s[10:11], 0, v57
	v_cmp_gt_i32_e64 s[12:13], v58, v57
	v_mad_u32_u24 v205, v57, v53, v52
	s_nop 0
	v_cndmask_b32_e64 v206, 0, v53, s[10:11]
	v_cndmask_b32_e64 v207, 0, v53, s[12:13]
	v_cndmask_b32_e64 v60, 0, 1.0, s[10:11]
	v_cndmask_b32_e64 v61, 0, 1.0, s[12:13]
	v_sub_u32_e32 v206, v205, v206
	v_add_u32_e32 v207, v205, v207
	global_load_dwordx4 v[64:67], v205, s[72:73] offset:-2048
	global_load_dwordx4 v[68:71], v205, s[72:73]
	global_load_dwordx4 v[72:75], v205, s[72:73] offset:2048
	global_load_dwordx4 v[76:79], v206, s[72:73] offset:-2048
	global_load_dwordx4 v[80:83], v206, s[72:73]
	global_load_dwordx4 v[84:87], v206, s[72:73] offset:2048
	global_load_dwordx4 v[88:91], v207, s[72:73] offset:-2048
	global_load_dwordx4 v[92:95], v207, s[72:73]
	global_load_dwordx4 v[96:99], v207, s[72:73] offset:2048
.Lmy_kpa_ni:
	v_mul_f32_e32 v160, v0, v208
	v_mul_f32_e32 v161, v1, v209
	v_mul_f32_e32 v162, v2, v210
	v_mul_f32_e32 v163, v3, v211
	v_mul_f32_e32 v164, v4, v212
	v_mul_f32_e32 v165, v5, v213
	v_mul_f32_e32 v166, v6, v214
	v_mul_f32_e32 v167, v7, v215
	v_mul_f32_e32 v200, v160, v160
	v_fmac_f32_e32 v200, v161, v161
	v_fmac_f32_e32 v200, v162, v162
	v_fmac_f32_e32 v200, v163, v163
	v_fmac_f32_e32 v200, v164, v164
	v_fmac_f32_e32 v200, v165, v165
	v_fmac_f32_e32 v200, v166, v166
	v_fmac_f32_e32 v200, v167, v167
	s_waitcnt lgkmcnt(0)
	v_add_f32_e32 v192, -1.0, v184
	v_fma_f32 v192, v8, v192, 1.0
	v_mul_f32_e32 v176, v208, v192
	v_add_f32_dpp v200, v200, v200 quad_perm:[1,0,3,2] row_mask:0xf bank_mask:0xf bound_ctrl:1
	v_add_f32_e32 v192, -1.0, v185
	v_fma_f32 v192, v9, v192, 1.0
	v_mul_f32_e32 v177, v209, v192
	v_add_f32_dpp v200, v200, v200 quad_perm:[2,3,0,1] row_mask:0xf bank_mask:0xf bound_ctrl:1
	v_add_f32_e32 v192, -1.0, v186
	v_fma_f32 v192, v10, v192, 1.0
	v_mul_f32_e32 v178, v210, v192
	v_add_f32_dpp v200, v200, v200 row_half_mirror row_mask:0xf bank_mask:0xf bound_ctrl:1
	v_add_f32_e32 v192, -1.0, v187
	v_fma_f32 v192, v11, v192, 1.0
	v_mul_f32_e32 v179, v211, v192
	v_add_f32_e32 v192, -1.0, v188
	v_fma_f32 v192, v12, v192, 1.0
	v_mul_f32_e32 v180, v212, v192
	v_add_f32_e32 v192, -1.0, v189
	v_fma_f32 v192, v13, v192, 1.0
	v_mul_f32_e32 v181, v213, v192
	v_add_f32_e32 v192, -1.0, v190
	v_fma_f32 v192, v14, v192, 1.0
	v_mul_f32_e32 v182, v214, v192
	v_add_f32_e32 v192, -1.0, v191
	v_fma_f32 v192, v15, v192, 1.0
	v_mul_f32_e32 v183, v215, v192
	v_max_f32_e32 v200, v200, v200
	v_max_f32_e32 v200, 0x179abe15, v200
	v_rsq_f32_e32 v201, v200
	v_mul_f32_e32 v192, v136, v176
	v_mul_f32_e32 v202, v16, v192
	v_mul_f32_e32 v160, v160, v201
	v_mul_f32_e32 v161, v161, v201
	v_mul_f32_e32 v162, v162, v201
	v_mul_f32_e32 v163, v163, v201
	v_mul_f32_e32 v164, v164, v201
	v_mul_f32_e32 v165, v165, v201
	v_mul_f32_e32 v166, v166, v201
	v_mul_f32_e32 v167, v167, v201
	v_mul_f32_e32 v168, v184, v160
	v_mul_f32_e32 v169, v185, v161
	v_mul_f32_e32 v170, v186, v162
	v_mul_f32_e32 v171, v187, v163
	v_mul_f32_e32 v172, v188, v164
	v_mul_f32_e32 v173, v189, v165
	v_mul_f32_e32 v174, v190, v166
	v_mul_f32_e32 v175, v191, v167
	ds_write_b128 v54, v[160:163] offset:0
	ds_write_b128 v54, v[164:167] offset:16
	ds_write_b128 v54, v[168:171] offset:256
	ds_write_b128 v54, v[172:175] offset:272
	ds_write_b128 v54, v[176:179] offset:512
	ds_write_b128 v54, v[180:183] offset:528
	ds_write_b128 v54, v[136:139] offset:768
	ds_write_b128 v54, v[140:143] offset:784
	ds_write_b128 v54, v[152:155] offset:1024
	ds_write_b128 v54, v[156:159] offset:1040
	v_mul_f32_e32 v192, v137, v177
	v_fmac_f32_e32 v202, v17, v192
	v_mul_f32_e32 v192, v138, v178
	v_fmac_f32_e32 v202, v18, v192
	v_mul_f32_e32 v192, v139, v179
	v_fmac_f32_e32 v202, v19, v192
	v_mul_f32_e32 v192, v140, v180
	v_fmac_f32_e32 v202, v20, v192
	v_mul_f32_e32 v192, v141, v181
	v_fmac_f32_e32 v202, v21, v192
	v_mul_f32_e32 v192, v142, v182
	v_fmac_f32_e32 v202, v22, v192
	v_mul_f32_e32 v192, v143, v183
	v_fmac_f32_e32 v202, v23, v192
	s_nop 1
	v_add_f32_dpp v202, v202, v202 quad_perm:[1,0,3,2] row_mask:0xf bank_mask:0xf bound_ctrl:1
	s_nop 1
	v_add_f32_dpp v202, v202, v202 quad_perm:[2,3,0,1] row_mask:0xf bank_mask:0xf bound_ctrl:1
	s_nop 1
	v_add_f32_dpp v202, v202, v202 row_half_mirror row_mask:0xf bank_mask:0xf bound_ctrl:1
	v_lshl_add_u32 v205, v56, 7, s60
	s_and_saveexec_b64 s[6:7], s[8:9]
	global_store_dword v205, v202, s[24:25]
	s_or_b64 exec, exec, s[6:7]
	v_add_u32_e32 v56, v59, v56
	s_waitcnt lgkmcnt(0)
	s_barrier
	s_add_i32 s66, s66, 1
	ds_read_b128 v[184:187], v55 offset:4096
	ds_read_b128 v[188:191], v55 offset:4112
	s_cmp_lt_u32 s66, 1024
	s_cbranch_scc0 .Lmy_kpb_w0
	s_waitcnt vmcnt(9)
	s_branch .Lmy_kpb_w1

.Lmy_kpb_w1:
	v_lshlrev_b32_e32 v136, 16, v100
	v_lshlrev_b32_e32 v192, 16, v112
	v_lshlrev_b32_e32 v193, 16, v124
	v_mul_f32_e32 v193, v63, v193
	v_fmac_f32_e32 v193, v62, v192
	v_fma_f32 v192, v193, 0.5, -v136
	v_fmac_f32_e32 v136, v24, v192
	v_and_b32_e32 v137, 0xffff0000, v100
	v_and_b32_e32 v192, 0xffff0000, v112
	v_and_b32_e32 v193, 0xffff0000, v124
	v_mul_f32_e32 v193, v63, v193
	v_fmac_f32_e32 v193, v62, v192
	v_fma_f32 v192, v193, 0.5, -v137
	v_fmac_f32_e32 v137, v25, v192
	v_lshlrev_b32_e32 v138, 16, v101
	v_lshlrev_b32_e32 v192, 16, v113
	v_lshlrev_b32_e32 v193, 16, v125
	v_mul_f32_e32 v193, v63, v193
	v_fmac_f32_e32 v193, v62, v192
	v_fma_f32 v192, v193, 0.5, -v138
	v_fmac_f32_e32 v138, v26, v192
	v_and_b32_e32 v139, 0xffff0000, v101
	v_and_b32_e32 v192, 0xffff0000, v113
	v_and_b32_e32 v193, 0xffff0000, v125
	v_mul_f32_e32 v193, v63, v193
	v_fmac_f32_e32 v193, v62, v192
	v_fma_f32 v192, v193, 0.5, -v139
	v_fmac_f32_e32 v139, v27, v192
	v_lshlrev_b32_e32 v140, 16, v102
	v_lshlrev_b32_e32 v192, 16, v114
	v_lshlrev_b32_e32 v193, 16, v126
	v_mul_f32_e32 v193, v63, v193
	v_fmac_f32_e32 v193, v62, v192
	v_fma_f32 v192, v193, 0.5, -v140
	v_fmac_f32_e32 v140, v28, v192
	v_and_b32_e32 v141, 0xffff0000, v102
	v_and_b32_e32 v192, 0xffff0000, v114
	v_and_b32_e32 v193, 0xffff0000, v126
	v_mul_f32_e32 v193, v63, v193
	v_fmac_f32_e32 v193, v62, v192
	v_fma_f32 v192, v193, 0.5, -v141
	v_fmac_f32_e32 v141, v29, v192
	v_lshlrev_b32_e32 v142, 16, v103
	v_lshlrev_b32_e32 v192, 16, v115
	v_lshlrev_b32_e32 v193, 16, v127
	v_mul_f32_e32 v193, v63, v193
	v_fmac_f32_e32 v193, v62, v192
	v_fma_f32 v192, v193, 0.5, -v142
	v_fmac_f32_e32 v142, v30, v192
	v_and_b32_e32 v143, 0xffff0000, v103
	v_and_b32_e32 v192, 0xffff0000, v115
	v_and_b32_e32 v193, 0xffff0000, v127
	v_mul_f32_e32 v193, v63, v193
	v_fmac_f32_e32 v193, v62, v192
	v_fma_f32 v192, v193, 0.5, -v143
	v_fmac_f32_e32 v143, v31, v192
	v_lshlrev_b32_e32 v208, 16, v104
	v_lshlrev_b32_e32 v192, 16, v116
	v_lshlrev_b32_e32 v193, 16, v128
	v_mul_f32_e32 v193, v63, v193
	v_fmac_f32_e32 v193, v62, v192
	v_fma_f32 v192, v193, 0.5, -v208
	v_fmac_f32_e32 v208, v32, v192
	v_and_b32_e32 v209, 0xffff0000, v104
	v_and_b32_e32 v192, 0xffff0000, v116
	v_and_b32_e32 v193, 0xffff0000, v128
	v_mul_f32_e32 v193, v63, v193
	v_fmac_f32_e32 v193, v62, v192
	v_fma_f32 v192, v193, 0.5, -v209
	v_fmac_f32_e32 v209, v33, v192
	v_lshlrev_b32_e32 v210, 16, v105
	v_lshlrev_b32_e32 v192, 16, v117
	v_lshlrev_b32_e32 v193, 16, v129
	v_mul_f32_e32 v193, v63, v193
	v_fmac_f32_e32 v193, v62, v192
	v_fma_f32 v192, v193, 0.5, -v210
	v_fmac_f32_e32 v210, v34, v192
	v_and_b32_e32 v211, 0xffff0000, v105
	v_and_b32_e32 v192, 0xffff0000, v117
	v_and_b32_e32 v193, 0xffff0000, v129
	v_mul_f32_e32 v193, v63, v193
	v_fmac_f32_e32 v193, v62, v192
	v_fma_f32 v192, v193, 0.5, -v211
	v_fmac_f32_e32 v211, v35, v192
	v_lshlrev_b32_e32 v212, 16, v106
	v_lshlrev_b32_e32 v192, 16, v118
	v_lshlrev_b32_e32 v193, 16, v130
	v_mul_f32_e32 v193, v63, v193
	v_fmac_f32_e32 v193, v62, v192
	v_fma_f32 v192, v193, 0.5, -v212
	v_fmac_f32_e32 v212, v36, v192
	v_and_b32_e32 v213, 0xffff0000, v106
	v_and_b32_e32 v192, 0xffff0000, v118
	v_and_b32_e32 v193, 0xffff0000, v130
	v_mul_f32_e32 v193, v63, v193
	v_fmac_f32_e32 v193, v62, v192
	v_fma_f32 v192, v193, 0.5, -v213
	v_fmac_f32_e32 v213, v37, v192
	v_lshlrev_b32_e32 v214, 16, v107
	v_lshlrev_b32_e32 v192, 16, v119
	v_lshlrev_b32_e32 v193, 16, v131
	v_mul_f32_e32 v193, v63, v193
	v_fmac_f32_e32 v193, v62, v192
	v_fma_f32 v192, v193, 0.5, -v214
	v_fmac_f32_e32 v214, v38, v192
	v_and_b32_e32 v215, 0xffff0000, v107
	v_and_b32_e32 v192, 0xffff0000, v119
	v_and_b32_e32 v193, 0xffff0000, v131
	v_mul_f32_e32 v193, v63, v193
	v_fmac_f32_e32 v193, v62, v192
	v_fma_f32 v192, v193, 0.5, -v215
	v_fmac_f32_e32 v215, v39, v192
	v_lshlrev_b32_e32 v152, 16, v108
	v_lshlrev_b32_e32 v192, 16, v120
	v_lshlrev_b32_e32 v193, 16, v132
	v_mul_f32_e32 v193, v63, v193
	v_fmac_f32_e32 v193, v62, v192
	v_fma_f32 v192, v193, 0.5, -v152
	v_fmac_f32_e32 v152, v40, v192
	v_and_b32_e32 v153, 0xffff0000, v108
	v_and_b32_e32 v192, 0xffff0000, v120
	v_and_b32_e32 v193, 0xffff0000, v132
	v_mul_f32_e32 v193, v63, v193
	v_fmac_f32_e32 v193, v62, v192
	v_fma_f32 v192, v193, 0.5, -v153
	v_fmac_f32_e32 v153, v41, v192
	v_lshlrev_b32_e32 v154, 16, v109
	v_lshlrev_b32_e32 v192, 16, v121
	v_lshlrev_b32_e32 v193, 16, v133
	v_mul_f32_e32 v193, v63, v193
	v_fmac_f32_e32 v193, v62, v192
	v_fma_f32 v192, v193, 0.5, -v154
	v_fmac_f32_e32 v154, v42, v192
	v_and_b32_e32 v155, 0xffff0000, v109
	v_and_b32_e32 v192, 0xffff0000, v121
	v_and_b32_e32 v193, 0xffff0000, v133
	v_mul_f32_e32 v193, v63, v193
	v_fmac_f32_e32 v193, v62, v192
	v_fma_f32 v192, v193, 0.5, -v155
	v_fmac_f32_e32 v155, v43, v192
	v_lshlrev_b32_e32 v156, 16, v110
	v_lshlrev_b32_e32 v192, 16, v122
	v_lshlrev_b32_e32 v193, 16, v134
	v_mul_f32_e32 v193, v63, v193
	v_fmac_f32_e32 v193, v62, v192
	v_fma_f32 v192, v193, 0.5, -v156
	v_fmac_f32_e32 v156, v44, v192
	v_and_b32_e32 v157, 0xffff0000, v110
	v_and_b32_e32 v192, 0xffff0000, v122
	v_and_b32_e32 v193, 0xffff0000, v134
	v_mul_f32_e32 v193, v63, v193
	v_fmac_f32_e32 v193, v62, v192
	v_fma_f32 v192, v193, 0.5, -v157
	v_fmac_f32_e32 v157, v45, v192
	v_lshlrev_b32_e32 v158, 16, v111
	v_lshlrev_b32_e32 v192, 16, v123
	v_lshlrev_b32_e32 v193, 16, v135
	v_mul_f32_e32 v193, v63, v193
	v_fmac_f32_e32 v193, v62, v192
	v_fma_f32 v192, v193, 0.5, -v158
	v_fmac_f32_e32 v158, v46, v192
	v_and_b32_e32 v159, 0xffff0000, v111
	v_and_b32_e32 v192, 0xffff0000, v123
	v_and_b32_e32 v193, 0xffff0000, v135
	v_mul_f32_e32 v193, v63, v193
	v_fmac_f32_e32 v193, v62, v192
	v_fma_f32 v192, v193, 0.5, -v159
	v_fmac_f32_e32 v159, v47, v192
	s_cmp_lt_u32 s66, 1023
	s_cbranch_scc0 .Lmy_kpb_ni
	v_add_u32_e32 v57, v59, v56
	v_add_u32_e32 v57, v59, v57
	v_cmp_lt_i32_e64 s[10:11], 0, v57
	v_cmp_gt_i32_e64 s[12:13], v58, v57
	v_mad_u32_u24 v205, v57, v53, v52
	s_nop 0
	v_cndmask_b32_e64 v206, 0, v53, s[10:11]
	v_cndmask_b32_e64 v207, 0, v53, s[12:13]
	v_cndmask_b32_e64 v62, 0, 1.0, s[10:11]
	v_cndmask_b32_e64 v63, 0, 1.0, s[12:13]
	v_sub_u32_e32 v206, v205, v206
	v_add_u32_e32 v207, v205, v207
	global_load_dwordx4 v[100:103], v205, s[72:73] offset:-2048
	global_load_dwordx4 v[104:107], v205, s[72:73]
	global_load_dwordx4 v[108:111], v205, s[72:73] offset:2048
	global_load_dwordx4 v[112:115], v206, s[72:73] offset:-2048
	global_load_dwordx4 v[116:119], v206, s[72:73]
	global_load_dwordx4 v[120:123], v206, s[72:73] offset:2048
	global_load_dwordx4 v[124:127], v207, s[72:73] offset:-2048
	global_load_dwordx4 v[128:131], v207, s[72:73]
	global_load_dwordx4 v[132:135], v207, s[72:73] offset:2048
.Lmy_kpb_ni:
	v_mul_f32_e32 v160, v0, v208
	v_mul_f32_e32 v161, v1, v209
	v_mul_f32_e32 v162, v2, v210
	v_mul_f32_e32 v163, v3, v211
	v_mul_f32_e32 v164, v4, v212
	v_mul_f32_e32 v165, v5, v213
	v_mul_f32_e32 v166, v6, v214
	v_mul_f32_e32 v167, v7, v215
	v_mul_f32_e32 v200, v160, v160
	v_fmac_f32_e32 v200, v161, v161
	v_fmac_f32_e32 v200, v162, v162
	v_fmac_f32_e32 v200, v163, v163
	v_fmac_f32_e32 v200, v164, v164
	v_fmac_f32_e32 v200, v165, v165
	v_fmac_f32_e32 v200, v166, v166
	v_fmac_f32_e32 v200, v167, v167
	s_waitcnt lgkmcnt(0)
	v_add_f32_e32 v192, -1.0, v184
	v_fma_f32 v192, v8, v192, 1.0
	v_mul_f32_e32 v176, v208, v192
	v_add_f32_dpp v200, v200, v200 quad_perm:[1,0,3,2] row_mask:0xf bank_mask:0xf bound_ctrl:1
	v_add_f32_e32 v192, -1.0, v185
	v_fma_f32 v192, v9, v192, 1.0
	v_mul_f32_e32 v177, v209, v192
	v_add_f32_dpp v200, v200, v200 quad_perm:[2,3,0,1] row_mask:0xf bank_mask:0xf bound_ctrl:1
	v_add_f32_e32 v192, -1.0, v186
	v_fma_f32 v192, v10, v192, 1.0
	v_mul_f32_e32 v178, v210, v192
	v_add_f32_dpp v200, v200, v200 row_half_mirror row_mask:0xf bank_mask:0xf bound_ctrl:1
	v_add_f32_e32 v192, -1.0, v187
	v_fma_f32 v192, v11, v192, 1.0
	v_mul_f32_e32 v179, v211, v192
	v_add_f32_e32 v192, -1.0, v188
	v_fma_f32 v192, v12, v192, 1.0
	v_mul_f32_e32 v180, v212, v192
	v_add_f32_e32 v192, -1.0, v189
	v_fma_f32 v192, v13, v192, 1.0
	v_mul_f32_e32 v181, v213, v192
	v_add_f32_e32 v192, -1.0, v190
	v_fma_f32 v192, v14, v192, 1.0
	v_mul_f32_e32 v182, v214, v192
	v_add_f32_e32 v192, -1.0, v191
	v_fma_f32 v192, v15, v192, 1.0
	v_mul_f32_e32 v183, v215, v192
	v_max_f32_e32 v200, v200, v200
	v_max_f32_e32 v200, 0x179abe15, v200
	v_rsq_f32_e32 v201, v200
	v_mul_f32_e32 v192, v136, v176
	v_mul_f32_e32 v202, v16, v192
	v_mul_f32_e32 v160, v160, v201
	v_mul_f32_e32 v161, v161, v201
	v_mul_f32_e32 v162, v162, v201
	v_mul_f32_e32 v163, v163, v201
	v_mul_f32_e32 v164, v164, v201
	v_mul_f32_e32 v165, v165, v201
	v_mul_f32_e32 v166, v166, v201
	v_mul_f32_e32 v167, v167, v201
	v_mul_f32_e32 v168, v184, v160
	v_mul_f32_e32 v169, v185, v161
	v_mul_f32_e32 v170, v186, v162
	v_mul_f32_e32 v171, v187, v163
	v_mul_f32_e32 v172, v188, v164
	v_mul_f32_e32 v173, v189, v165
	v_mul_f32_e32 v174, v190, v166
	v_mul_f32_e32 v175, v191, v167
	ds_write_b128 v54, v[160:163] offset:20480
	ds_write_b128 v54, v[164:167] offset:20496
	ds_write_b128 v54, v[168:171] offset:20736
	ds_write_b128 v54, v[172:175] offset:20752
	ds_write_b128 v54, v[176:179] offset:20992
	ds_write_b128 v54, v[180:183] offset:21008
	ds_write_b128 v54, v[136:139] offset:21248
	ds_write_b128 v54, v[140:143] offset:21264
	ds_write_b128 v54, v[152:155] offset:21504
	ds_write_b128 v54, v[156:159] offset:21520
	v_mul_f32_e32 v192, v137, v177
	v_fmac_f32_e32 v202, v17, v192
	v_mul_f32_e32 v192, v138, v178
	v_fmac_f32_e32 v202, v18, v192
	v_mul_f32_e32 v192, v139, v179
	v_fmac_f32_e32 v202, v19, v192
	v_mul_f32_e32 v192, v140, v180
	v_fmac_f32_e32 v202, v20, v192
	v_mul_f32_e32 v192, v141, v181
	v_fmac_f32_e32 v202, v21, v192
	v_mul_f32_e32 v192, v142, v182
	v_fmac_f32_e32 v202, v22, v192
	v_mul_f32_e32 v192, v143, v183
	v_fmac_f32_e32 v202, v23, v192
	s_nop 1
	v_add_f32_dpp v202, v202, v202 quad_perm:[1,0,3,2] row_mask:0xf bank_mask:0xf bound_ctrl:1
	s_nop 1
	v_add_f32_dpp v202, v202, v202 quad_perm:[2,3,0,1] row_mask:0xf bank_mask:0xf bound_ctrl:1
	s_nop 1
	v_add_f32_dpp v202, v202, v202 row_half_mirror row_mask:0xf bank_mask:0xf bound_ctrl:1
	v_lshl_add_u32 v205, v56, 7, s60
	s_and_saveexec_b64 s[6:7], s[8:9]
	global_store_dword v205, v202, s[24:25]
	s_or_b64 exec, exec, s[6:7]
	v_add_u32_e32 v56, v59, v56
	s_waitcnt lgkmcnt(0)
	s_barrier
	s_add_i32 s66, s66, 1
	s_cmp_lt_u32 s66, 1025
	s_cbranch_scc1 .Lmy_kp_loop
	s_waitcnt lgkmcnt(0)
	s_barrier
